# int8 up K-loop: MFMA order k-innermost (same-accumulator pairs adjacent, acc forwarding)
# speedup vs baseline: 1.0018x; 1.0018x over previous
.LBB0_292:
	s_add_u32 s36, s28, s34
	s_addc_u32 s37, s29, s35
	s_add_u32 s36, s36, 0x100
	s_addc_u32 s37, s37, 0
	s_add_u32 s77, s27, s34
	s_addc_u32 s78, s31, s35
	s_cmpk_eq_i32 s34, 0x700
	s_cselect_b32 s43, s21, s37
	s_cselect_b32 s42, s74, s36
	s_cselect_b32 s37, s17, s78
	s_cselect_b32 s36, s75, s77
	s_setprio 1
	s_waitcnt lgkmcnt(0)
	v_mfma_i32_16x16x64_i8 v[128:131], v[148:151], v[188:191], v[128:131]
	v_mfma_i32_16x16x64_i8 v[128:131], v[152:155], v[192:195], v[128:131]
	v_mfma_i32_16x16x64_i8 v[120:123], v[156:159], v[188:191], v[120:123]
	v_mfma_i32_16x16x64_i8 v[120:123], v[160:163], v[192:195], v[120:123]
	v_mfma_i32_16x16x64_i8 v[112:115], v[148:151], v[180:183], v[112:115]
	v_mfma_i32_16x16x64_i8 v[112:115], v[152:155], v[184:187], v[112:115]
	v_mfma_i32_16x16x64_i8 v[104:107], v[156:159], v[180:183], v[104:107]
	v_mfma_i32_16x16x64_i8 v[104:107], v[160:163], v[184:187], v[104:107]
	v_mfma_i32_16x16x64_i8 v[96:99], v[148:151], v[172:175], v[96:99]
	v_mfma_i32_16x16x64_i8 v[96:99], v[152:155], v[176:179], v[96:99]
	v_mfma_i32_16x16x64_i8 v[88:91], v[156:159], v[172:175], v[88:91]
	v_mfma_i32_16x16x64_i8 v[88:91], v[160:163], v[176:179], v[88:91]
	v_mfma_i32_16x16x64_i8 v[80:83], v[148:151], v[164:167], v[80:83]
	v_mfma_i32_16x16x64_i8 v[80:83], v[152:155], v[168:171], v[80:83]
	v_mfma_i32_16x16x64_i8 v[72:75], v[156:159], v[164:167], v[72:75]
	v_mfma_i32_16x16x64_i8 v[72:75], v[160:163], v[168:171], v[72:75]
	s_setprio 0
	s_setprio 1
	v_mfma_i32_16x16x64_i8 v[124:127], v[132:135], v[188:191], v[124:127]
	v_mfma_i32_16x16x64_i8 v[124:127], v[136:139], v[192:195], v[124:127]
	v_mfma_i32_16x16x64_i8 v[116:119], v[140:143], v[188:191], v[116:119]
	v_mfma_i32_16x16x64_i8 v[116:119], v[144:147], v[192:195], v[116:119]
	v_mfma_i32_16x16x64_i8 v[108:111], v[132:135], v[180:183], v[108:111]
	v_mfma_i32_16x16x64_i8 v[108:111], v[136:139], v[184:187], v[108:111]
	v_mfma_i32_16x16x64_i8 v[100:103], v[140:143], v[180:183], v[100:103]
	v_mfma_i32_16x16x64_i8 v[100:103], v[144:147], v[184:187], v[100:103]
	v_mfma_i32_16x16x64_i8 v[92:95], v[132:135], v[172:175], v[92:95]
	v_mfma_i32_16x16x64_i8 v[92:95], v[136:139], v[176:179], v[92:95]
	v_mfma_i32_16x16x64_i8 v[84:87], v[140:143], v[172:175], v[84:87]
	v_mfma_i32_16x16x64_i8 v[84:87], v[144:147], v[176:179], v[84:87]
	v_mfma_i32_16x16x64_i8 v[76:79], v[132:135], v[164:167], v[76:79]
	v_mfma_i32_16x16x64_i8 v[76:79], v[136:139], v[168:171], v[76:79]
	v_mfma_i32_16x16x64_i8 v[68:71], v[140:143], v[164:167], v[68:71]
	v_mfma_i32_16x16x64_i8 v[68:71], v[144:147], v[168:171], v[68:71]
	s_setprio 0
	s_barrier
	s_mov_b32 m0, s64
	v_lshl_add_u64 v[246:247], s[36:37], 0, v[34:35]
	s_add_u32 vcc_lo, s36, 0x40000
	ds_read_b128 v[164:167], v244 offset:16384
	ds_read_b128 v[168:171], v244 offset:17408
	ds_read_b128 v[172:175], v244 offset:18432
	ds_read_b128 v[176:179], v244 offset:19456
	ds_read_b128 v[180:183], v244 offset:20480
	ds_read_b128 v[184:187], v244 offset:21504
	ds_read_b128 v[188:191], v244 offset:22528
	ds_read_b128 v[192:195], v244 offset:23552
	global_load_lds_dwordx4 v[246:247], off
	v_lshl_add_u64 v[248:249], s[36:37], 0, v[210:211]
	s_mov_b32 m0, s65
	s_addc_u32 vcc_hi, s37, 0
	global_load_lds_dwordx4 v[248:249], off
	v_lshl_add_u64 v[250:251], vcc, 0, v[34:35]
	s_mov_b32 m0, s66
	v_lshl_add_u64 v[198:199], s[42:43], 0, v[208:209]
	global_load_lds_dwordx4 v[250:251], off
	v_lshl_add_u64 v[250:251], vcc, 0, v[210:211]
	s_mov_b32 m0, s67
	s_nop 0
	global_load_lds_dwordx4 v[250:251], off
	v_lshl_add_u64 v[250:251], s[42:43], 0, v[206:207]
	s_mov_b32 m0, s63
	s_nop 0
	global_load_lds_dwordx4 v[250:251], off
	s_mov_b32 m0, s68
	s_nop 0
	global_load_lds_dwordx4 v[198:199], off
	s_waitcnt vmcnt(8)
	s_waitcnt lgkmcnt(0)
	s_barrier
	s_setprio 1
	s_waitcnt lgkmcnt(0)
	v_mfma_i32_16x16x64_i8 v[64:67], v[148:151], v[164:167], v[64:67]
	v_mfma_i32_16x16x64_i8 v[64:67], v[152:155], v[168:171], v[64:67]
	v_mfma_i32_16x16x64_i8 v[56:59], v[156:159], v[164:167], v[56:59]
	v_mfma_i32_16x16x64_i8 v[56:59], v[160:163], v[168:171], v[56:59]
	v_mfma_i32_16x16x64_i8 v[48:51], v[148:151], v[172:175], v[48:51]
	v_mfma_i32_16x16x64_i8 v[48:51], v[152:155], v[176:179], v[48:51]
	v_mfma_i32_16x16x64_i8 v[40:43], v[156:159], v[172:175], v[40:43]
	v_mfma_i32_16x16x64_i8 v[40:43], v[160:163], v[176:179], v[40:43]
	v_mfma_i32_16x16x64_i8 v[30:33], v[148:151], v[180:183], v[30:33]
	v_mfma_i32_16x16x64_i8 v[30:33], v[152:155], v[184:187], v[30:33]
	v_mfma_i32_16x16x64_i8 v[22:25], v[156:159], v[180:183], v[22:25]
	v_mfma_i32_16x16x64_i8 v[22:25], v[160:163], v[184:187], v[22:25]
	v_mfma_i32_16x16x64_i8 v[14:17], v[148:151], v[188:191], v[14:17]
	v_mfma_i32_16x16x64_i8 v[14:17], v[152:155], v[192:195], v[14:17]
	v_mfma_i32_16x16x64_i8 v[6:9], v[156:159], v[188:191], v[6:9]
	v_mfma_i32_16x16x64_i8 v[6:9], v[160:163], v[192:195], v[6:9]
	s_setprio 0
	s_setprio 1
	v_mfma_i32_16x16x64_i8 v[60:63], v[132:135], v[164:167], v[60:63]
	v_mfma_i32_16x16x64_i8 v[60:63], v[136:139], v[168:171], v[60:63]
	v_mfma_i32_16x16x64_i8 v[52:55], v[140:143], v[164:167], v[52:55]
	v_mfma_i32_16x16x64_i8 v[52:55], v[144:147], v[168:171], v[52:55]
	v_mfma_i32_16x16x64_i8 v[44:47], v[132:135], v[172:175], v[44:47]
	v_mfma_i32_16x16x64_i8 v[44:47], v[136:139], v[176:179], v[44:47]
	v_mfma_i32_16x16x64_i8 v[36:39], v[140:143], v[172:175], v[36:39]
	v_mfma_i32_16x16x64_i8 v[36:39], v[144:147], v[176:179], v[36:39]
	v_mfma_i32_16x16x64_i8 v[26:29], v[132:135], v[180:183], v[26:29]
	v_mfma_i32_16x16x64_i8 v[26:29], v[136:139], v[184:187], v[26:29]
	v_mfma_i32_16x16x64_i8 v[18:21], v[140:143], v[180:183], v[18:21]
	v_mfma_i32_16x16x64_i8 v[18:21], v[144:147], v[184:187], v[18:21]
	v_mfma_i32_16x16x64_i8 v[10:13], v[132:135], v[188:191], v[10:13]
	v_mfma_i32_16x16x64_i8 v[10:13], v[136:139], v[192:195], v[10:13]
	v_mfma_i32_16x16x64_i8 v[2:5], v[140:143], v[188:191], v[2:5]
	v_mfma_i32_16x16x64_i8 v[2:5], v[144:147], v[192:195], v[2:5]
	s_setprio 0
	s_barrier
	s_add_i32 s77, 0, 0x18000
	s_add_i32 s78, 0, 0x1c000
	v_add_u32_e32 v144, s77, v243
	v_add_u32_e32 v160, s78, v243
	ds_read_b128 v[132:135], v144
	ds_read_b128 v[136:139], v144 offset:1024
	ds_read_b128 v[140:143], v144 offset:2048
	ds_read_b128 v[144:147], v144 offset:3072
	ds_read_b128 v[148:151], v160
	ds_read_b128 v[152:155], v160 offset:1024
	ds_read_b128 v[156:159], v160 offset:2048
	ds_read_b128 v[160:163], v160 offset:3072
	s_add_u32 s42, s42, 0x40000
	s_addc_u32 s43, s43, 0
	s_mov_b32 m0, s69
	v_lshl_add_u64 v[200:201], s[42:43], 0, v[206:207]
	ds_read_b128 v[164:167], v244 offset:32768
	ds_read_b128 v[168:171], v244 offset:33792
	ds_read_b128 v[172:175], v244 offset:34816
	ds_read_b128 v[176:179], v244 offset:35840
	ds_read_b128 v[180:183], v244 offset:36864
	ds_read_b128 v[184:187], v244 offset:37888
	ds_read_b128 v[188:191], v244 offset:38912
	ds_read_b128 v[192:195], v244 offset:39936
	global_load_lds_dwordx4 v[200:201], off
	v_lshl_add_u64 v[200:201], s[42:43], 0, v[208:209]
	s_mov_b32 m0, s70
	s_nop 0
	global_load_lds_dwordx4 v[200:201], off
	s_waitcnt vmcnt(8)
	s_waitcnt lgkmcnt(0)
	s_barrier
	s_setprio 1
	s_waitcnt lgkmcnt(0)
	v_mfma_i32_16x16x64_i8 v[128:131], v[132:135], v[164:167], v[128:131]
	v_mfma_i32_16x16x64_i8 v[128:131], v[136:139], v[168:171], v[128:131]
	v_mfma_i32_16x16x64_i8 v[120:123], v[140:143], v[164:167], v[120:123]
	v_mfma_i32_16x16x64_i8 v[120:123], v[144:147], v[168:171], v[120:123]
	v_mfma_i32_16x16x64_i8 v[112:115], v[132:135], v[172:175], v[112:115]
	v_mfma_i32_16x16x64_i8 v[112:115], v[136:139], v[176:179], v[112:115]
	v_mfma_i32_16x16x64_i8 v[104:107], v[140:143], v[172:175], v[104:107]
	v_mfma_i32_16x16x64_i8 v[104:107], v[144:147], v[176:179], v[104:107]
	v_mfma_i32_16x16x64_i8 v[96:99], v[132:135], v[180:183], v[96:99]
	v_mfma_i32_16x16x64_i8 v[96:99], v[136:139], v[184:187], v[96:99]
	v_mfma_i32_16x16x64_i8 v[88:91], v[140:143], v[180:183], v[88:91]
	v_mfma_i32_16x16x64_i8 v[88:91], v[144:147], v[184:187], v[88:91]
	v_mfma_i32_16x16x64_i8 v[80:83], v[132:135], v[188:191], v[80:83]
	v_mfma_i32_16x16x64_i8 v[80:83], v[136:139], v[192:195], v[80:83]
	v_mfma_i32_16x16x64_i8 v[72:75], v[140:143], v[188:191], v[72:75]
	v_mfma_i32_16x16x64_i8 v[72:75], v[144:147], v[192:195], v[72:75]
	s_setprio 0
	s_setprio 1
	v_mfma_i32_16x16x64_i8 v[124:127], v[148:151], v[164:167], v[124:127]
	v_mfma_i32_16x16x64_i8 v[124:127], v[152:155], v[168:171], v[124:127]
	v_mfma_i32_16x16x64_i8 v[116:119], v[156:159], v[164:167], v[116:119]
	v_mfma_i32_16x16x64_i8 v[116:119], v[160:163], v[168:171], v[116:119]
	v_mfma_i32_16x16x64_i8 v[108:111], v[148:151], v[172:175], v[108:111]
	v_mfma_i32_16x16x64_i8 v[108:111], v[152:155], v[176:179], v[108:111]
	v_mfma_i32_16x16x64_i8 v[100:103], v[156:159], v[172:175], v[100:103]
	v_mfma_i32_16x16x64_i8 v[100:103], v[160:163], v[176:179], v[100:103]
	v_mfma_i32_16x16x64_i8 v[92:95], v[148:151], v[180:183], v[92:95]
	v_mfma_i32_16x16x64_i8 v[92:95], v[152:155], v[184:187], v[92:95]
	v_mfma_i32_16x16x64_i8 v[84:87], v[156:159], v[180:183], v[84:87]
	v_mfma_i32_16x16x64_i8 v[84:87], v[160:163], v[184:187], v[84:87]
	v_mfma_i32_16x16x64_i8 v[76:79], v[148:151], v[188:191], v[76:79]
	v_mfma_i32_16x16x64_i8 v[76:79], v[152:155], v[192:195], v[76:79]
	v_mfma_i32_16x16x64_i8 v[68:71], v[156:159], v[188:191], v[68:71]
	v_mfma_i32_16x16x64_i8 v[68:71], v[160:163], v[192:195], v[68:71]
	s_setprio 0
	s_barrier
	s_add_i32 s42, s77, s62
	v_lshl_add_u64 v[200:201], v[246:247], 0, s[18:19]
	s_mov_b32 m0, s42
	ds_read_b128 v[164:167], v244 offset:49152
	ds_read_b128 v[168:171], v244 offset:50176
	ds_read_b128 v[172:175], v244 offset:51200
	ds_read_b128 v[176:179], v244 offset:52224
	ds_read_b128 v[180:183], v244 offset:53248
	ds_read_b128 v[184:187], v244 offset:54272
	ds_read_b128 v[188:191], v244 offset:55296
	ds_read_b128 v[192:195], v244 offset:56320
	global_load_lds_dwordx4 v[200:201], off
	s_add_i32 m0, s42, 0x2000
	s_add_u32 s36, s36, 0x40080
	v_lshl_add_u64 v[200:201], v[248:249], 0, s[18:19]
	s_addc_u32 s37, s37, 0
	s_add_i32 s42, s78, s62
	global_load_lds_dwordx4 v[200:201], off
	v_lshl_add_u64 v[200:201], s[36:37], 0, v[34:35]
	s_mov_b32 m0, s42
	v_lshl_add_u64 v[198:199], v[198:199], 0, s[18:19]
	global_load_lds_dwordx4 v[200:201], off
	v_lshl_add_u64 v[200:201], s[36:37], 0, v[210:211]
	s_add_i32 m0, s42, 0x2000
	s_nop 0
	global_load_lds_dwordx4 v[200:201], off
	v_lshl_add_u64 v[200:201], v[250:251], 0, s[18:19]
	s_mov_b32 m0, s71
	s_nop 0
	global_load_lds_dwordx4 v[200:201], off
	s_mov_b32 m0, s72
	s_nop 0
	global_load_lds_dwordx4 v[198:199], off
	s_waitcnt vmcnt(8)
	s_waitcnt lgkmcnt(0)
	s_barrier
	s_setprio 1
	s_waitcnt lgkmcnt(0)
	v_mfma_i32_16x16x64_i8 v[64:67], v[132:135], v[164:167], v[64:67]
	v_mfma_i32_16x16x64_i8 v[64:67], v[136:139], v[168:171], v[64:67]
	v_mfma_i32_16x16x64_i8 v[56:59], v[140:143], v[164:167], v[56:59]
	v_mfma_i32_16x16x64_i8 v[56:59], v[144:147], v[168:171], v[56:59]
	v_mfma_i32_16x16x64_i8 v[48:51], v[132:135], v[172:175], v[48:51]
	v_mfma_i32_16x16x64_i8 v[48:51], v[136:139], v[176:179], v[48:51]
	v_mfma_i32_16x16x64_i8 v[40:43], v[140:143], v[172:175], v[40:43]
	v_mfma_i32_16x16x64_i8 v[40:43], v[144:147], v[176:179], v[40:43]
	v_mfma_i32_16x16x64_i8 v[30:33], v[132:135], v[180:183], v[30:33]
	v_mfma_i32_16x16x64_i8 v[30:33], v[136:139], v[184:187], v[30:33]
	v_mfma_i32_16x16x64_i8 v[22:25], v[140:143], v[180:183], v[22:25]
	v_mfma_i32_16x16x64_i8 v[22:25], v[144:147], v[184:187], v[22:25]
	v_mfma_i32_16x16x64_i8 v[14:17], v[132:135], v[188:191], v[14:17]
	v_mfma_i32_16x16x64_i8 v[14:17], v[136:139], v[192:195], v[14:17]
	v_mfma_i32_16x16x64_i8 v[6:9], v[140:143], v[188:191], v[6:9]
	v_mfma_i32_16x16x64_i8 v[6:9], v[144:147], v[192:195], v[6:9]
	s_setprio 0
	s_setprio 1
	v_mfma_i32_16x16x64_i8 v[60:63], v[148:151], v[164:167], v[60:63]
	v_mfma_i32_16x16x64_i8 v[60:63], v[152:155], v[168:171], v[60:63]
	v_mfma_i32_16x16x64_i8 v[52:55], v[156:159], v[164:167], v[52:55]
	v_mfma_i32_16x16x64_i8 v[52:55], v[160:163], v[168:171], v[52:55]
	v_mfma_i32_16x16x64_i8 v[44:47], v[148:151], v[172:175], v[44:47]
	v_mfma_i32_16x16x64_i8 v[44:47], v[152:155], v[176:179], v[44:47]
	v_mfma_i32_16x16x64_i8 v[36:39], v[156:159], v[172:175], v[36:39]
	v_mfma_i32_16x16x64_i8 v[36:39], v[160:163], v[176:179], v[36:39]
	v_mfma_i32_16x16x64_i8 v[26:29], v[148:151], v[180:183], v[26:29]
	v_mfma_i32_16x16x64_i8 v[26:29], v[152:155], v[184:187], v[26:29]
	v_mfma_i32_16x16x64_i8 v[18:21], v[156:159], v[180:183], v[18:21]
	v_mfma_i32_16x16x64_i8 v[18:21], v[160:163], v[184:187], v[18:21]
	v_mfma_i32_16x16x64_i8 v[10:13], v[148:151], v[188:191], v[10:13]
	v_mfma_i32_16x16x64_i8 v[10:13], v[152:155], v[192:195], v[10:13]
	v_mfma_i32_16x16x64_i8 v[2:5], v[156:159], v[188:191], v[2:5]
	v_mfma_i32_16x16x64_i8 v[2:5], v[160:163], v[192:195], v[2:5]
	s_setprio 0
	s_barrier
	s_add_i32 s76, s76, 2
	s_add_u32 s34, s34, 0x100
	s_addc_u32 s35, s35, 0
	s_cmp_gt_u32 s76, 13
	s_cbranch_scc1 .LBB0_295
